# v69 + during the grid barriers before the four later GEMM phases, waves 4-7 touch the first K-tiles of the CU's first weight tile (warm-up while wave 0 spins)
# speedup vs baseline: 1.0095x; 1.0029x over previous
.LBB0_747:
	s_waitcnt vmcnt(0)
	s_barrier
	v_readfirstlane_b32 s6, v202
	s_cmp_lt_u32 s6, 0x100
	s_cbranch_scc1 .Lwpf_end_0
	s_cmp_lg_u32 s88, 0x100
	s_cbranch_scc1 .Lwpf_end_0
	v_readlane_b32 s7, v248, 5
	v_add_u32_e32 v0, 0xffffff00, v202
	s_lshr_b32 s7, s7, 6
	s_lshl_b32 s7, s7, 8
	s_mov_b32 s6, 0xc00
	v_add_u32_e32 v0, s7, v0
	v_mul_lo_u32 v0, v0, s6
	v_add_u32_e32 v0, 0xf00000, v0
	global_load_dword v2, v0, s[78:79]
	global_load_dword v2, v0, s[78:79] offset:128
	global_load_dword v2, v0, s[78:79] offset:256
	global_load_dword v2, v0, s[78:79] offset:384
.Lwpf_end_0:
	s_and_saveexec_b64 s[0:1], s[96:97]
	v_readlane_b32 s70, v249, 23
	v_readlane_b32 s80, v249, 25
	v_readlane_b32 s71, v249, 24
	v_readlane_b32 s81, v249, 26
	s_cbranch_execz .LBB0_799
	s_add_i32 s2, 0, 0x20160
	v_mov_b32_e32 v0, s2
	s_waitcnt vmcnt(0) expcnt(0) lgkmcnt(0)
	ds_read_b32 v2, v0
	s_add_i32 s2, 0, 0x20164
	v_mov_b32_e32 v0, s2
	ds_read_b32 v0, v0
	s_waitcnt lgkmcnt(1)
	v_cmp_ne_u32_e32 vcc, 0, v2
	s_cbranch_vccnz .LBB0_763
	v_readlane_b32 s2, v249, 0
	s_mul_i32 s33, s89, s2
	s_add_u32 s2, s78, 0x100200
	s_addc_u32 s3, s79, 0
	s_add_u32 s4, s78, 0x100400
	s_addc_u32 s5, s79, 0
	s_add_u32 s6, s78, 0x100500
	s_addc_u32 s7, s79, 0
	s_add_u32 s8, s78, 0x100600
	s_addc_u32 s9, s79, 0
	s_add_u32 s10, s78, 0x100700
	s_addc_u32 s11, s79, 0
	s_add_u32 s12, s78, 0x100800
	s_addc_u32 s13, s79, 0
	s_add_u32 s14, s78, 0x100900
	s_addc_u32 s15, s79, 0
	s_add_u32 s16, s78, 0x100a00
	s_addc_u32 s17, s79, 0
	s_add_u32 s18, s78, 0x100b00
	s_addc_u32 s19, s79, 0
	s_add_u32 s20, s78, 0x100c00
	s_addc_u32 s21, s79, 0
	s_add_u32 s22, s78, 0x100d00
	s_addc_u32 s23, s79, 0
	s_add_u32 s24, s78, 0x100e00
	s_addc_u32 s25, s79, 0
	s_add_u32 s26, s78, 0x100f00
	s_addc_u32 s27, s79, 0
	s_add_u32 s28, s78, 0x101000
	s_addc_u32 s29, s79, 0
	s_add_u32 s30, s78, 0x101100
	s_addc_u32 s31, s79, 0
	s_add_u32 s34, s78, 0x101200
	s_addc_u32 s35, s79, 0
	s_add_u32 s36, s78, 0x101300
	s_mul_i32 s33, s33, s88
	s_addc_u32 s37, s79, 0
	s_mov_b32 s44, 1
	v_mov_b32_e32 v16, 0
	s_branch .LBB0_751

.LBB0_829:
	s_waitcnt vmcnt(0)
	s_barrier
	v_readfirstlane_b32 s6, v202
	s_cmp_lt_u32 s6, 0x100
	s_cbranch_scc1 .Lwpf_end_1
	s_cmp_lg_u32 s88, 0x100
	s_cbranch_scc1 .Lwpf_end_1
	v_readlane_b32 s7, v248, 5
	v_add_u32_e32 v0, 0xffffff00, v202
	s_lshr_b32 s7, s7, 6
	s_lshl_b32 s7, s7, 8
	s_mov_b32 s6, 0x800
	v_add_u32_e32 v0, s7, v0
	v_mul_lo_u32 v0, v0, s6
	v_add_u32_e32 v0, 0x1200000, v0
	global_load_dword v2, v0, s[78:79]
	global_load_dword v2, v0, s[78:79] offset:128
	global_load_dword v2, v0, s[78:79] offset:256
	global_load_dword v2, v0, s[78:79] offset:384
.Lwpf_end_1:
	s_and_saveexec_b64 s[0:1], s[96:97]
	s_cbranch_execz .LBB0_881
	s_add_i32 s4, 0, 0x20160
	v_mov_b32_e32 v0, s4
	s_waitcnt vmcnt(0) expcnt(0) lgkmcnt(0)
	ds_read_b32 v2, v0
	s_add_i32 s4, 0, 0x20164
	v_mov_b32_e32 v0, s4
	ds_read_b32 v0, v0
	s_waitcnt lgkmcnt(1)
	v_cmp_ne_u32_e32 vcc, 0, v2
	s_cbranch_vccnz .LBB0_845
	v_readlane_b32 s4, v249, 0
	s_mul_i32 s33, s89, s4
	s_add_u32 s4, s78, 0x100200
	s_addc_u32 s5, s79, 0
	s_add_u32 s6, s78, 0x100400
	s_addc_u32 s7, s79, 0
	s_add_u32 s8, s78, 0x100500
	s_addc_u32 s9, s79, 0
	s_add_u32 s10, s78, 0x100600
	s_addc_u32 s11, s79, 0
	s_add_u32 s12, s78, 0x100700
	s_addc_u32 s13, s79, 0
	s_add_u32 s14, s78, 0x100800
	s_addc_u32 s15, s79, 0
	s_add_u32 s16, s78, 0x100900
	s_addc_u32 s17, s79, 0
	s_add_u32 s18, s78, 0x100a00
	s_addc_u32 s19, s79, 0
	s_add_u32 s20, s78, 0x100b00
	s_addc_u32 s21, s79, 0
	s_add_u32 s22, s78, 0x100c00
	s_addc_u32 s23, s79, 0
	s_add_u32 s24, s78, 0x100d00
	s_addc_u32 s25, s79, 0
	s_add_u32 s26, s78, 0x100e00
	s_addc_u32 s27, s79, 0
	s_add_u32 s28, s78, 0x100f00
	s_addc_u32 s29, s79, 0
	s_add_u32 s30, s78, 0x101000
	s_addc_u32 s31, s79, 0
	s_add_u32 s34, s78, 0x101100
	s_addc_u32 s35, s79, 0
	s_add_u32 s36, s78, 0x101200
	s_addc_u32 s37, s79, 0
	s_add_u32 s38, s78, 0x101300
	s_mul_i32 s33, s33, s88
	s_addc_u32 s39, s79, 0
	s_mov_b32 s46, 1
	v_mov_b32_e32 v16, 0
	s_branch .LBB0_833

.LBB0_923:
	s_waitcnt vmcnt(0)
	s_waitcnt lgkmcnt(0)
	s_barrier
	v_readfirstlane_b32 s6, v202
	s_cmp_lt_u32 s6, 0x100
	s_cbranch_scc1 .Lwpf_end_2
	s_cmp_lg_u32 s88, 0x100
	s_cbranch_scc1 .Lwpf_end_2
	v_readlane_b32 s7, v248, 5
	v_add_u32_e32 v0, 0xffffff00, v202
	s_lshr_b32 s7, s7, 6
	s_lshl_b32 s7, s7, 8
	s_mov_b32 s6, 0x800
	v_add_u32_e32 v0, s7, v0
	v_mul_lo_u32 v0, v0, s6
	v_add_u32_e32 v0, 0x1400000, v0
	global_load_dword v2, v0, s[78:79]
	global_load_dword v2, v0, s[78:79] offset:128
	global_load_dword v2, v0, s[78:79] offset:256
	global_load_dword v2, v0, s[78:79] offset:384
.Lwpf_end_2:
	s_and_saveexec_b64 s[2:3], s[96:97]
	s_cbranch_execz .LBB0_975
	s_add_i32 s4, 0, 0x20160
	v_mov_b32_e32 v0, s4
	s_waitcnt vmcnt(0) expcnt(0) lgkmcnt(0)
	ds_read_b32 v2, v0
	s_add_i32 s4, 0, 0x20164
	v_mov_b32_e32 v0, s4
	ds_read_b32 v0, v0
	s_waitcnt lgkmcnt(1)
	v_cmp_ne_u32_e32 vcc, 0, v2
	s_cbranch_vccnz .LBB0_939
	v_readlane_b32 s4, v249, 0
	s_mul_i32 s33, s89, s4
	s_add_u32 s4, s78, 0x100200
	s_addc_u32 s5, s79, 0
	s_add_u32 s6, s78, 0x100400
	s_addc_u32 s7, s79, 0
	s_add_u32 s8, s78, 0x100500
	s_addc_u32 s9, s79, 0
	s_add_u32 s10, s78, 0x100600
	s_addc_u32 s11, s79, 0
	s_add_u32 s12, s78, 0x100700
	s_addc_u32 s13, s79, 0
	s_add_u32 s14, s78, 0x100800
	s_addc_u32 s15, s79, 0
	s_add_u32 s16, s78, 0x100900
	s_addc_u32 s17, s79, 0
	s_add_u32 s18, s78, 0x100a00
	s_addc_u32 s19, s79, 0
	s_add_u32 s20, s78, 0x100b00
	s_addc_u32 s21, s79, 0
	s_add_u32 s22, s78, 0x100c00
	s_addc_u32 s23, s79, 0
	s_add_u32 s24, s78, 0x100d00
	s_addc_u32 s25, s79, 0
	s_add_u32 s26, s78, 0x100e00
	s_addc_u32 s27, s79, 0
	s_add_u32 s28, s78, 0x100f00
	s_addc_u32 s29, s79, 0
	s_add_u32 s30, s78, 0x101000
	s_addc_u32 s31, s79, 0
	s_add_u32 s34, s78, 0x101100
	s_addc_u32 s35, s79, 0
	s_add_u32 s36, s78, 0x101200
	s_addc_u32 s37, s79, 0
	s_add_u32 s38, s78, 0x101300
	s_mul_i32 s33, s33, s88
	s_addc_u32 s39, s79, 0
	s_mov_b32 s46, 1
	v_mov_b32_e32 v16, 0
	s_branch .LBB0_927

.LBB0_1001:
	s_waitcnt vmcnt(0)
	s_barrier
	v_readfirstlane_b32 s6, v202
	s_cmp_lt_u32 s6, 0x100
	s_cbranch_scc1 .Lwpf_end_3
	s_cmp_lg_u32 s88, 0x100
	s_cbranch_scc1 .Lwpf_end_3
	v_readlane_b32 s7, v248, 5
	v_add_u32_e32 v0, 0xffffff00, v202
	s_lshr_b32 s7, s7, 6
	s_lshl_b32 s7, s7, 8
	s_mov_b32 s6, 0x2000
	v_add_u32_e32 v0, s7, v0
	v_mul_lo_u32 v0, v0, s6
	v_add_u32_e32 v0, 0x1c00000, v0
	global_load_dword v2, v0, s[78:79]
	global_load_dword v2, v0, s[78:79] offset:128
	global_load_dword v2, v0, s[78:79] offset:256
	global_load_dword v2, v0, s[78:79] offset:384
